# strategy 7.12: wave-uniform rescale test shortened (v_cmp feeds the branch directly), rare rescale blocks moved out of line
# baseline (speedup 1.0000x reference)
; __device__ __forceinline__ void attn_unit_a(FLAS unsigned char* lds, const Unit u) {
;     ...
;         if (first || __any(rm > 8.0f)) {
;             const float dl = __builtin_fmaxf(rm, first ? -1000.0f : 0.0f); const float f = first ? 1.0f : __builtin_amdgcn_exp2f(-dl);
;             mrun = first ? dl : mrun + dl; lsum *= f; fpend = f; pend = !first; first = false;
; #pragma unroll
;             for (int r = 0; r < 16; ++r) { pC0[r] = pC0[r] - dl; pC1[r] = pC1[r] - dl; }
;         }
.LBB0_440:
	v_bfrev_b32_e32 v141, 1
	s_mov_b32 s12, 0xc47a0000
	s_branch .LBB0_441
.Lresc_e:
	s_mov_b32 s12, 0
	v_mov_b32_e32 v141, v211
.LBB0_441:
	v_max_f32_e64 v142, s12, s12
	v_max_f32_e32 v140, v140, v140
	v_max_f32_e32 v140, v140, v142
	v_exp_f32_e64 v142, -v140
	v_add_f32_e32 v211, v141, v140
	v_sub_f32_e32 v111, v111, v140
	v_sub_f32_e32 v110, v110, v140
	v_cndmask_b32_e64 v226, v142, 1.0, s[24:25]
	v_mul_f32_e32 v212, v212, v226
	v_sub_f32_e32 v109, v109, v140
	v_sub_f32_e32 v108, v108, v140
	v_sub_f32_e32 v107, v107, v140
	v_sub_f32_e32 v106, v106, v140
	v_sub_f32_e32 v105, v105, v140
	v_sub_f32_e32 v104, v104, v140
	v_sub_f32_e32 v103, v103, v140
	v_sub_f32_e32 v102, v102, v140
	v_sub_f32_e32 v101, v101, v140
	v_sub_f32_e32 v100, v100, v140
	v_sub_f32_e32 v99, v99, v140
	v_sub_f32_e32 v98, v98, v140
	v_sub_f32_e32 v97, v97, v140
	v_sub_f32_e32 v96, v96, v140
	v_sub_f32_e32 v127, v127, v140
	v_sub_f32_e32 v126, v126, v140
	v_sub_f32_e32 v125, v125, v140
	v_sub_f32_e32 v124, v124, v140
	v_sub_f32_e32 v123, v123, v140
	v_sub_f32_e32 v122, v122, v140
	v_sub_f32_e32 v121, v121, v140
	v_sub_f32_e32 v120, v120, v140
	v_sub_f32_e32 v119, v119, v140
	v_sub_f32_e32 v118, v118, v140
	v_sub_f32_e32 v117, v117, v140
	v_sub_f32_e32 v116, v116, v140
	v_sub_f32_e32 v115, v115, v140
	v_sub_f32_e32 v114, v114, v140
	v_sub_f32_e32 v113, v113, v140
	v_sub_f32_e32 v112, v112, v140
	s_branch .LBB0_442
.Lresc_o:
	s_mov_b64 s[0:1], -1
	v_max_f32_e32 v96, v96, v96
	v_max_f32_e32 v96, 0, v96
	v_exp_f32_e64 v226, -v96
	v_add_f32_e32 v211, v211, v96
	v_sub_f32_e32 v64, v64, v96
	v_sub_f32_e32 v65, v65, v96
	v_mul_f32_e32 v212, v212, v226
	v_sub_f32_e32 v66, v66, v96
	v_sub_f32_e32 v67, v67, v96
	v_sub_f32_e32 v68, v68, v96
	v_sub_f32_e32 v69, v69, v96
	v_sub_f32_e32 v70, v70, v96
	v_sub_f32_e32 v71, v71, v96
	v_sub_f32_e32 v72, v72, v96
	v_sub_f32_e32 v73, v73, v96
	v_sub_f32_e32 v74, v74, v96
	v_sub_f32_e32 v75, v75, v96
	v_sub_f32_e32 v76, v76, v96
	v_sub_f32_e32 v77, v77, v96
	v_sub_f32_e32 v78, v78, v96
	v_sub_f32_e32 v79, v79, v96
	v_sub_f32_e32 v80, v80, v96
	v_sub_f32_e32 v81, v81, v96
	v_sub_f32_e32 v82, v82, v96
	v_sub_f32_e32 v83, v83, v96
	v_sub_f32_e32 v84, v84, v96
	v_sub_f32_e32 v85, v85, v96
	v_sub_f32_e32 v86, v86, v96
	v_sub_f32_e32 v87, v87, v96
	v_sub_f32_e32 v88, v88, v96
	v_sub_f32_e32 v89, v89, v96
	v_sub_f32_e32 v90, v90, v96
	v_sub_f32_e32 v91, v91, v96
	v_sub_f32_e32 v92, v92, v96
	v_sub_f32_e32 v93, v93, v96
	v_sub_f32_e32 v94, v94, v96
	v_sub_f32_e32 v95, v95, v96
	s_branch .LBB0_462

; #define FLAS __attribute__((address_space(3)))
; __device__ __forceinline__ void attn_unit_a(FLAS unsigned char* lds, const Unit u) {
;     ...
;         const int vsp = (i == 0) ? 0 : ((i - 1) & 3);
;         const FLAS unsigned char* vb_ = lds + LA_V + vsp * VBUF + r32 * VPITCH + hi * 16;
;         const FLAS unsigned char* kb = lds + LA_K + ((i + 1) & 1) * KBUF;
;     ...
;         u32x4 vr[3];
; #pragma unroll
;         for (int m = 0; m < 3; ++m) vr[m] = FA_VFRAG(m);
;         const float off = cbC - mrun;
;         FA_SB();
;         float ra, rb, rm;
;         FA_PVM(0); pC0[0] = fadd_s(pC0[0], off); pC1[0] = fadd_s(pC1[0], off); pC0[1] = fadd_s(pC0[1], off); pC1[1] = fadd_s(pC1[1], off); pC0[2] = fadd_s(pC0[2], off); pC1[2] = fadd_s(pC1[2], off); FA_SB();
;         FA_PVM(1); ra = __builtin_fmaxf(__builtin_fmaxf(pC0[0], pC0[1]), pC0[2]); rb = __builtin_fmaxf(__builtin_fmaxf(pC1[0], pC1[1]), pC1[2]); pC0[3] = fadd_s(pC0[3], off); pC1[3] = fadd_s(pC1[3], off); pC0[4] = fadd_s(pC0[4], off); pC1[4] = fadd_s(pC1[4], off); FA_SB();
;         FA_PVM(2); ra = __builtin_fmaxf(__builtin_fmaxf(ra, pC0[3]), pC0[4]); rb = __builtin_fmaxf(__builtin_fmaxf(rb, pC1[3]), pC1[4]); pC0[5] = fadd_s(pC0[5], off); pC1[5] = fadd_s(pC1[5], off); pC0[6] = fadd_s(pC0[6], off); pC1[6] = fadd_s(pC1[6], off); FA_SB();
;         FA_PVM(3); ra = __builtin_fmaxf(__builtin_fmaxf(ra, pC0[5]), pC0[6]); rb = __builtin_fmaxf(__builtin_fmaxf(rb, pC1[5]), pC1[6]); pC0[7] = fadd_s(pC0[7], off); pC1[7] = fadd_s(pC1[7], off); pC0[8] = fadd_s(pC0[8], off); pC1[8] = fadd_s(pC1[8], off); FA_SB();
;         FA_PVM(4); ra = __builtin_fmaxf(__builtin_fmaxf(ra, pC0[7]), pC0[8]); rb = __builtin_fmaxf(__builtin_fmaxf(rb, pC1[7]), pC1[8]); pC0[9] = fadd_s(pC0[9], off); pC1[9] = fadd_s(pC1[9], off); pC0[10] = fadd_s(pC0[10], off); pC1[10] = fadd_s(pC1[10], off); FA_SB();
;         FA_PVM(5); ra = __builtin_fmaxf(__builtin_fmaxf(ra, pC0[9]), pC0[10]); rb = __builtin_fmaxf(__builtin_fmaxf(rb, pC1[9]), pC1[10]); pC0[11] = fadd_s(pC0[11], off); pC1[11] = fadd_s(pC1[11], off); pC0[12] = fadd_s(pC0[12], off); pC1[12] = fadd_s(pC1[12], off); FA_SB();
;         FA_PVM(6); ra = __builtin_fmaxf(__builtin_fmaxf(ra, pC0[11]), pC0[12]); rb = __builtin_fmaxf(__builtin_fmaxf(rb, pC1[11]), pC1[12]); pC0[13] = fadd_s(pC0[13], off); pC1[13] = fadd_s(pC1[13], off); pC0[14] = fadd_s(pC0[14], off); pC1[14] = fadd_s(pC1[14], off); FA_SB();
.LBB0_437:
	s_add_i32 s12, s19, -1
	s_xor_b64 s[20:21], s[24:25], -1
	s_and_b32 s18, s12, 3
	s_mulk_i32 s18, 0x4800
	s_cmp_lg_u32 s49, 0
	s_cselect_b32 s12, s18, 0
	v_add_u32_e32 v200, s12, v251
	ds_read_b128 v[128:131], v200 offset:16384
	ds_read_b128 v[132:135], v200 offset:20992
	ds_read_b128 v[136:139], v200 offset:25600
	s_waitcnt lgkmcnt(2)
	v_mfma_f32_32x32x16_bf16 v[48:63], v[128:131], v[204:207], v[48:63]
	ds_read_b128 v[128:131], v200 offset:30208
	v_max3_f32 v140, v96, v97, v98
	v_max3_f32 v141, v112, v113, v114
	v_cvt_pk_bf16_f32 v196, v72, v73
	v_cvt_pk_bf16_f32 v197, v74, v75
	v_add_f32_e32 v212, v80, v212
	v_add_f32_e32 v212, v81, v212
	s_waitcnt lgkmcnt(2)
	v_mfma_f32_32x32x16_bf16 v[32:47], v[132:135], v[204:207], v[32:47]
	ds_read_b128 v[132:135], v200 offset:16416
	v_max3_f32 v140, v140, v99, v100
	v_max3_f32 v141, v141, v115, v116
	v_cvt_pk_bf16_f32 v198, v76, v77
	v_cvt_pk_bf16_f32 v199, v78, v79
	v_add_f32_e32 v212, v82, v212
	v_add_f32_e32 v212, v83, v212
	s_waitcnt lgkmcnt(2)
	v_mfma_f32_32x32x16_bf16 v[16:31], v[136:139], v[204:207], v[16:31]
	ds_read_b128 v[136:139], v200 offset:21024
	v_max3_f32 v140, v140, v101, v102
	v_max3_f32 v141, v141, v117, v118
	v_cvt_pk_bf16_f32 v192, v80, v81
	v_cvt_pk_bf16_f32 v193, v82, v83
	v_add_f32_e32 v212, v84, v212
	v_add_f32_e32 v212, v85, v212
	s_waitcnt lgkmcnt(2)
	v_mfma_f32_32x32x16_bf16 v[0:15], v[128:131], v[204:207], v[0:15]
	ds_read_b128 v[128:131], v200 offset:25632
	v_max3_f32 v140, v140, v103, v104
	v_max3_f32 v141, v141, v119, v120
	v_cvt_pk_bf16_f32 v194, v84, v85
	v_cvt_pk_bf16_f32 v195, v86, v87
	v_add_f32_e32 v212, v86, v212
	v_add_f32_e32 v212, v87, v212
	s_waitcnt lgkmcnt(2)
	v_mfma_f32_32x32x16_bf16 v[48:63], v[132:135], v[196:199], v[48:63]
	ds_read_b128 v[132:135], v200 offset:30240
	v_max3_f32 v140, v140, v105, v106
	v_max3_f32 v141, v141, v121, v122
	v_cvt_pk_bf16_f32 v188, v88, v89
	v_cvt_pk_bf16_f32 v189, v90, v91
	v_add_f32_e32 v212, v88, v212
	v_add_f32_e32 v212, v89, v212
	s_waitcnt lgkmcnt(2)
	v_mfma_f32_32x32x16_bf16 v[32:47], v[136:139], v[196:199], v[32:47]
	ds_read_b128 v[136:139], v200 offset:16448
	v_max3_f32 v140, v140, v107, v108
	v_max3_f32 v141, v141, v123, v124
	v_cvt_pk_bf16_f32 v190, v92, v93
	v_cvt_pk_bf16_f32 v191, v94, v95
	v_add_f32_e32 v212, v90, v212
	v_add_f32_e32 v212, v91, v212
	s_waitcnt lgkmcnt(2)
	v_mfma_f32_32x32x16_bf16 v[16:31], v[128:131], v[196:199], v[16:31]
	ds_read_b128 v[128:131], v200 offset:21056
	v_max3_f32 v140, v140, v109, v110
	v_max3_f32 v141, v141, v125, v126
	v_add_f32_e32 v212, v92, v212
	v_add_f32_e32 v212, v93, v212
	s_waitcnt lgkmcnt(2)
	v_mfma_f32_32x32x16_bf16 v[0:15], v[132:135], v[196:199], v[0:15]
	ds_read_b128 v[132:135], v200 offset:25664
	v_max3_f32 v140, v140, v141, v111
	v_max_f32_e32 v140, v140, v127
	v_add_f32_e32 v212, v94, v212
	v_add_f32_e32 v212, v95, v212
	v_mov_b32_e32 v141, v140
	s_nop 1
	v_permlane32_swap_b32 v140, v141
	s_nop 1
	s_nop 0
	v_max_f32_e32 v140, v140, v141
	s_andn2_b64 vcc, exec, s[20:21]
	s_cbranch_vccnz .LBB0_440
	v_cmp_lt_f32_e32 vcc, s39, v140
	s_cbranch_vccnz .Lresc_e
	s_mov_b64 s[20:21], 0

; #define FLAS __attribute__((address_space(3)))
; __device__ __forceinline__ void attn_unit_a(FLAS unsigned char* lds, const Unit u) {
;     ...
;         const int vsp = (i == 0) ? 0 : ((i - 1) & 3);
;         const FLAS unsigned char* vb_ = lds + LA_V + vsp * VBUF + r32 * VPITCH + hi * 16;
;         const FLAS unsigned char* kb = lds + LA_K + ((i + 1) & 1) * KBUF;
;     ...
;         u32x4 vr[3];
; #pragma unroll
;         for (int m = 0; m < 3; ++m) vr[m] = FA_VFRAG(m);
;         const float off = cbC - mrun;
;         FA_SB();
;         float ra, rb, rm;
;         FA_PVM(0); pC0[0] = fadd_s(pC0[0], off); pC1[0] = fadd_s(pC1[0], off); pC0[1] = fadd_s(pC0[1], off); pC1[1] = fadd_s(pC1[1], off); pC0[2] = fadd_s(pC0[2], off); pC1[2] = fadd_s(pC1[2], off); FA_SB();
;         FA_PVM(1); ra = __builtin_fmaxf(__builtin_fmaxf(pC0[0], pC0[1]), pC0[2]); rb = __builtin_fmaxf(__builtin_fmaxf(pC1[0], pC1[1]), pC1[2]); pC0[3] = fadd_s(pC0[3], off); pC1[3] = fadd_s(pC1[3], off); pC0[4] = fadd_s(pC0[4], off); pC1[4] = fadd_s(pC1[4], off); FA_SB();
;         FA_PVM(2); ra = __builtin_fmaxf(__builtin_fmaxf(ra, pC0[3]), pC0[4]); rb = __builtin_fmaxf(__builtin_fmaxf(rb, pC1[3]), pC1[4]); pC0[5] = fadd_s(pC0[5], off); pC1[5] = fadd_s(pC1[5], off); pC0[6] = fadd_s(pC0[6], off); pC1[6] = fadd_s(pC1[6], off); FA_SB();
;         FA_PVM(3); ra = __builtin_fmaxf(__builtin_fmaxf(ra, pC0[5]), pC0[6]); rb = __builtin_fmaxf(__builtin_fmaxf(rb, pC1[5]), pC1[6]); pC0[7] = fadd_s(pC0[7], off); pC1[7] = fadd_s(pC1[7], off); pC0[8] = fadd_s(pC0[8], off); pC1[8] = fadd_s(pC1[8], off); FA_SB();
;         FA_PVM(4); ra = __builtin_fmaxf(__builtin_fmaxf(ra, pC0[7]), pC0[8]); rb = __builtin_fmaxf(__builtin_fmaxf(rb, pC1[7]), pC1[8]); pC0[9] = fadd_s(pC0[9], off); pC1[9] = fadd_s(pC1[9], off); pC0[10] = fadd_s(pC0[10], off); pC1[10] = fadd_s(pC1[10], off); FA_SB();
;         FA_PVM(5); ra = __builtin_fmaxf(__builtin_fmaxf(ra, pC0[9]), pC0[10]); rb = __builtin_fmaxf(__builtin_fmaxf(rb, pC1[9]), pC1[10]); pC0[11] = fadd_s(pC0[11], off); pC1[11] = fadd_s(pC1[11], off); pC0[12] = fadd_s(pC0[12], off); pC1[12] = fadd_s(pC1[12], off); FA_SB();
;         FA_PVM(6); ra = __builtin_fmaxf(__builtin_fmaxf(ra, pC0[11]), pC0[12]); rb = __builtin_fmaxf(__builtin_fmaxf(rb, pC1[11]), pC1[12]); pC0[13] = fadd_s(pC0[13], off); pC1[13] = fadd_s(pC1[13], off); pC0[14] = fadd_s(pC0[14], off); pC1[14] = fadd_s(pC1[14], off); FA_SB();
.LBB0_460:
	s_and_b32 s0, s19, 2
	s_mulk_i32 s0, 0x4800
	v_add_u32_e32 v201, s0, v251
	v_cvt_pk_bf16_f32 v140, v96, v97
	v_cvt_pk_bf16_f32 v141, v98, v99
	v_cvt_pk_bf16_f32 v142, v100, v101
	v_cvt_pk_bf16_f32 v143, v102, v103
	ds_read_b128 v[128:131], v201 offset:16384
	ds_read_b128 v[132:135], v201 offset:20992
	ds_read_b128 v[136:139], v201 offset:25600
	s_waitcnt lgkmcnt(2)
	v_mfma_f32_32x32x16_bf16 v[48:63], v[128:131], v[140:143], v[48:63]
	ds_read_b128 v[128:131], v201 offset:30208
	v_max3_f32 v96, v64, v65, v66
	v_max3_f32 v97, v80, v81, v82
	v_cvt_pk_bf16_f32 v232, v104, v105
	v_cvt_pk_bf16_f32 v233, v106, v107
	v_add_f32_e32 v212, v112, v212
	v_add_f32_e32 v212, v113, v212
	s_waitcnt lgkmcnt(2)
	v_mfma_f32_32x32x16_bf16 v[32:47], v[132:135], v[140:143], v[32:47]
	ds_read_b128 v[132:135], v201 offset:16416
	v_max3_f32 v96, v96, v67, v68
	v_max3_f32 v97, v97, v83, v84
	v_cvt_pk_bf16_f32 v234, v108, v109
	v_cvt_pk_bf16_f32 v235, v110, v111
	v_add_f32_e32 v212, v114, v212
	v_add_f32_e32 v212, v115, v212
	s_waitcnt lgkmcnt(2)
	v_mfma_f32_32x32x16_bf16 v[16:31], v[136:139], v[140:143], v[16:31]
	ds_read_b128 v[136:139], v201 offset:21024
	v_max3_f32 v96, v96, v69, v70
	v_max3_f32 v97, v97, v85, v86
	v_add_f32_e32 v212, v116, v212
	v_add_f32_e32 v212, v117, v212
	s_waitcnt lgkmcnt(2)
	v_mfma_f32_32x32x16_bf16 v[0:15], v[128:131], v[140:143], v[0:15]
	ds_read_b128 v[128:131], v201 offset:25632
	v_max3_f32 v96, v96, v71, v72
	v_max3_f32 v97, v97, v87, v88
	v_add_f32_e32 v212, v118, v212
	v_add_f32_e32 v212, v119, v212
	s_waitcnt lgkmcnt(2)
	v_mfma_f32_32x32x16_bf16 v[48:63], v[132:135], v[232:235], v[48:63]
	ds_read_b128 v[132:135], v201 offset:30240
	v_max3_f32 v96, v96, v73, v74
	v_max3_f32 v97, v97, v89, v90
	v_cvt_pk_bf16_f32 v140, v112, v113
	v_cvt_pk_bf16_f32 v141, v114, v115
	v_add_f32_e32 v212, v120, v212
	v_add_f32_e32 v212, v121, v212
	s_waitcnt lgkmcnt(2)
	v_mfma_f32_32x32x16_bf16 v[32:47], v[136:139], v[232:235], v[32:47]
	ds_read_b128 v[136:139], v201 offset:16448
	v_max3_f32 v96, v96, v75, v76
	v_max3_f32 v97, v97, v91, v92
	v_cvt_pk_bf16_f32 v142, v116, v117
	v_cvt_pk_bf16_f32 v143, v118, v119
	v_add_f32_e32 v212, v122, v212
	v_add_f32_e32 v212, v123, v212
	s_waitcnt lgkmcnt(2)
	v_mfma_f32_32x32x16_bf16 v[16:31], v[128:131], v[232:235], v[16:31]
	ds_read_b128 v[128:131], v201 offset:21056
	v_max3_f32 v96, v96, v77, v78
	v_max3_f32 v97, v97, v93, v94
	v_add_f32_e32 v212, v124, v212
	v_add_f32_e32 v212, v125, v212
	s_waitcnt lgkmcnt(2)
	v_mfma_f32_32x32x16_bf16 v[0:15], v[132:135], v[232:235], v[0:15]
	ds_read_b128 v[132:135], v201 offset:25664
	v_max3_f32 v96, v96, v97, v79
	v_max_f32_e32 v96, v96, v95
	v_add_f32_e32 v212, v126, v212
	v_add_f32_e32 v212, v127, v212
	v_mov_b32_e32 v97, v96
	s_nop 1
	v_permlane32_swap_b32 v96, v97
	s_nop 1
	s_nop 0
	v_max_f32_e32 v96, v96, v97
	v_cmp_lt_f32_e32 vcc, s39, v96
	s_mov_b64 s[0:1], 0
	s_cbranch_vccnz .Lresc_o
